# batched gain transposes + 16-way K-tile swizzle in diff attention (both bit-exact) on top of v35
# speedup vs baseline: 1.0099x; 1.0099x over previous
; #define LAS __attribute__((address_space(3)))
; #define DF_EXP_A(p0, p1) do { _Pragma("unroll") for (int r = 0; r < 16; ++r) p0[r] = __builtin_amdgcn_exp2f(p0[r]); _Pragma("unroll") for (int r = 0; r < 8; ++r) p1[r] = __builtin_amdgcn_exp2f(p1[r]); } while (0)
; __device__ __forceinline__ void diff_unit(const PolDiff& P, LAS unsigned char* lds, const Ptrs& X) {
;     ...
;     { const int row = 4 * wid + (lane >> 4), c = (lane & 15) ^ (row & 7); gko = row * NQKV + P.kcol0() + 8 * c; }
;     { const int sidx = 2 * wid + (lane >> 5), kk = 8 * (sidx >> 2) + ((lane & 31) >> 2), k = (kk & ~0xC) | ((kk & 4) << 1) | ((kk & 8) >> 1), c = 32 * (sidx & 3) + 8 * (lane & 3);
;       gvo = k * NQKV + P.vcol0() + c; }
;     const bf16_t* gtile = qkv + (long)P.b * T * NQKV;
;     const LAS unsigned char* krd = K_lds + r32 * (W * 2);
;     ...
;     DF_GLDS(0, 0); DF_GLDS(1, 1); __syncthreads();
;     P.cinit_abs<0>(pA0, DF_TL(0), wid, r32, hi); P.cinit_abs<1>(pA1, DF_TL(0), wid, r32, hi); DF_QK(pA0, pA1, 0); DF_EXP_A(pA0, pA1);
.LBB0_269:
	v_lshrrev_b32_e32 v2, 4, v8
	v_lshl_or_b32 v2, s23, 2, v2
	v_and_b32_e32 v4, 15, v18
	s_movk_i32 s1, 0xc00
	v_bitop3_b32 v4, v2, v4, 15 bitop3:0x6c
	v_mul_lo_u32 v2, v2, s1
	s_ashr_i32 s3, s3, 4
	v_lshl_or_b32 v2, v4, 3, v2
	s_and_b32 s13, s3, 0x3ffff0
	v_lshrrev_b32_e32 v4, 2, v6
	v_lshrrev_b32_e32 v5, 1, v6
	s_lshr_b32 s3, s3, 1
	s_lshl_b32 s5, s23, 1
	v_and_or_b32 v4, v4, 3, s13
	v_and_b32_e32 v5, 8, v5
	s_and_b32 s3, s3, 4
	s_lshl_b32 s10, s10, 1
	v_or3_b32 v4, v4, v5, s3
	v_and_or_b32 v5, s5, 2, v7
	s_mul_i32 s2, s2, 0x1800000
	v_lshlrev_b32_e32 v5, 5, v5
	v_lshlrev_b32_e32 v9, 3, v18
	s_add_u32 s5, s94, s2
	v_add_u32_e32 v2, s40, v2
	v_mul_u32_u24_e32 v4, 0xc00, v4
	v_and_or_b32 v5, v9, 24, v5
	s_addc_u32 s31, s95, 0
	s_sub_i32 s38, s11, s4
	s_mul_i32 s2, s42, 0x1800
	v_lshlrev_b32_e32 v3, 1, v8
	v_add_u32_e32 v2, 0x400, v2
	v_or3_b32 v4, v5, s40, v4
	s_mul_hi_u32 s3, s42, 0x1800
	s_add_u32 s2, s5, s2
	v_add_u32_e32 v4, 0x800, v4
	v_lshlrev_b32_e32 v5, 4, v8
	v_and_b32_e32 v56, 32, v3
	s_addc_u32 s3, s31, s3
	v_ashrrev_i32_e32 v3, 31, v2
	s_lshl_b32 s11, s23, 10
	v_and_b32_e32 v55, 0xc0, v5
	v_lshlrev_b64 v[148:149], 1, v[2:3]
	v_ashrrev_i32_e32 v5, 31, v4
	s_add_i32 s39, s11, 0
	v_lshl_add_u64 v[2:3], s[2:3], 0, v[148:149]
	v_lshlrev_b64 v[150:151], 1, v[4:5]
	s_mov_b32 m0, s39
	s_barrier
	v_lshl_add_u64 v[4:5], s[2:3], 0, v[150:151]
	global_load_lds_dwordx4 v[2:3], off
	s_add_i32 m0, s39, 0xc000
	s_mov_b64 vcc, 0x30000
	global_load_lds_dwordx4 v[4:5], off
	v_lshl_add_u64 v[2:3], v[2:3], 0, vcc
	s_add_i32 m0, s39, 0x2000
	s_or_b32 s2, s42, 64
	global_load_lds_dwordx4 v[2:3], off
	s_add_i32 m0, s39, 0xe000
	s_mul_hi_u32 s3, s2, 0x1800
	s_mulk_i32 s2, 0x1800
	s_add_u32 s2, s5, s2
	v_lshl_add_u64 v[2:3], v[4:5], 0, vcc
	s_addc_u32 s3, s31, s3
	global_load_lds_dwordx4 v[2:3], off
	v_lshl_add_u64 v[2:3], s[2:3], 0, v[148:149]
	s_add_i32 m0, s39, 0x4000
	v_lshl_add_u64 v[4:5], s[2:3], 0, v[150:151]
	global_load_lds_dwordx4 v[2:3], off
	s_add_i32 m0, s39, 0x10000
	v_lshl_add_u64 v[2:3], v[2:3], 0, vcc
	global_load_lds_dwordx4 v[4:5], off
	s_add_i32 m0, s39, 0x6000
	v_mul_i32_i24_e32 v20, -4, v7
	global_load_lds_dwordx4 v[2:3], off
	v_lshl_add_u64 v[2:3], v[4:5], 0, vcc
	s_add_i32 m0, s39, 0x12000
	v_add3_u32 v57, v20, v6, s21
	global_load_lds_dwordx4 v[2:3], off
	v_add_u32_e32 v2, -1, v57
	v_cvt_f32_i32_e32 v21, v2
	v_add_u32_e32 v3, -3, v57
	v_cvt_f32_i32_e32 v22, v3
	v_add_u32_e32 v5, -9, v57
	v_and_b32_e32 v3, 0x7fffffff, v21
	v_or_b32_e32 v21, 0xffffffe0, v18
	v_add_u32_e32 v7, -11, v57
	v_subrev_u32_e32 v9, 17, v57
	v_subrev_u32_e32 v11, 19, v57
	v_subrev_u32_e32 v13, 25, v57
	v_subrev_u32_e32 v15, 27, v57
	v_add3_u32 v58, v20, v21, s21
	v_cvt_f32_i32_e32 v17, v15
	v_cvt_f32_i32_e32 v15, v13
	v_cvt_f32_i32_e32 v13, v11
	v_cvt_f32_i32_e32 v11, v9
	v_cvt_f32_i32_e32 v9, v7
	v_cvt_f32_i32_e32 v7, v5
	v_cvt_f32_i32_e32 v5, v57
	v_add_u32_e32 v20, -1, v58
	v_add_u32_e32 v23, -9, v58
	v_add_u32_e32 v24, -8, v58
	v_subrev_u32_e32 v34, 26, v58
	v_cvt_f32_i32_e32 v59, v34
	v_cvt_f32_i32_e32 v34, v24
	v_cvt_f32_i32_e32 v24, v23
	v_cvt_f32_i32_e32 v23, v58
	v_cvt_f32_i32_e32 v20, v20
	v_lshlrev_b32_e32 v18, 4, v18
	v_and_b32_e32 v18, 0xf0, v18
	v_lshl_add_u32 v182, v6, 8, 0
	v_subrev_u32_e32 v27, 17, v58
	v_bitop3_b32 v186, s10, v18, v0 bitop3:0x36
	v_and_b32_e32 v2, 0x7fffffff, v5
	v_and_b32_e32 v5, 0x7fffffff, v22
	v_add_u32_e32 v21, -3, v58
	v_add_u32_e32 v22, -2, v58
	v_add_u32_e32 v25, -11, v58
	v_add_u32_e32 v26, -10, v58
	v_subrev_u32_e32 v32, 24, v58
	v_subrev_u32_e32 v33, 27, v58
	v_cvt_f32_i32_e32 v38, v27
	v_add_u32_e32 v27, v182, v186
	s_waitcnt vmcnt(0) lgkmcnt(0)
	s_barrier
	v_cvt_f32_i32_e32 v60, v33
	v_cvt_f32_i32_e32 v52, v32
	v_cvt_f32_i32_e32 v32, v26
	v_cvt_f32_i32_e32 v33, v25
	v_cvt_f32_i32_e32 v25, v22
	v_cvt_f32_i32_e32 v26, v21
	v_and_b32_e32 v40, 0x7fffffff, v23
	v_and_b32_e32 v41, 0x7fffffff, v20
	ds_read_b128 v[20:23], v27
	v_add_u32_e32 v4, -2, v57
	v_add_u32_e32 v6, -8, v57
	v_add_u32_e32 v8, -10, v57
	v_add_u32_e32 v10, -16, v57
	v_subrev_u32_e32 v12, 18, v57
	v_subrev_u32_e32 v14, 24, v57
	v_subrev_u32_e32 v16, 26, v57
	v_cvt_f32_i32_e32 v16, v16
	v_cvt_f32_i32_e32 v14, v14
	v_cvt_f32_i32_e32 v12, v12
	v_cvt_f32_i32_e32 v10, v10
	v_cvt_f32_i32_e32 v8, v8
	v_cvt_f32_i32_e32 v6, v6
	v_cvt_f32_i32_e32 v4, v4
	v_or_b32_e32 v0, s10, v0
	v_bitop3_b32 v187, v0, v18, 32 bitop3:0x36
	v_and_b32_e32 v7, 0x7fffffff, v7
	v_and_b32_e32 v4, 0x7fffffff, v4
	v_and_b32_e32 v6, 0x7fffffff, v6
	v_and_b32_e32 v9, 0x7fffffff, v9
	v_and_b32_e32 v8, 0x7fffffff, v8
	v_and_b32_e32 v11, 0x7fffffff, v11
	v_and_b32_e32 v10, 0x7fffffff, v10
	v_and_b32_e32 v13, 0x7fffffff, v13
	v_and_b32_e32 v12, 0x7fffffff, v12
	v_and_b32_e32 v15, 0x7fffffff, v15
	v_and_b32_e32 v14, 0x7fffffff, v14
	v_and_b32_e32 v17, 0x7fffffff, v17
	v_and_b32_e32 v16, 0x7fffffff, v16
	v_add_u32_e32 v28, -16, v58
	v_subrev_u32_e32 v29, 19, v58
	v_subrev_u32_e32 v30, 18, v58
	v_subrev_u32_e32 v31, 25, v58
	v_add_u32_e32 v35, v182, v187
	v_pk_mul_f32 v[16:17], v[200:201], v[16:17] op_sel_hi:[0,1]
	v_pk_mul_f32 v[14:15], v[200:201], v[14:15] op_sel_hi:[0,1]
	v_pk_mul_f32 v[12:13], v[200:201], v[12:13] op_sel_hi:[0,1]
	v_pk_mul_f32 v[10:11], v[200:201], v[10:11] op_sel_hi:[0,1]
	v_pk_mul_f32 v[8:9], v[200:201], v[8:9] op_sel_hi:[0,1]
	v_pk_mul_f32 v[6:7], v[200:201], v[6:7] op_sel_hi:[0,1]
	v_pk_mul_f32 v[4:5], v[200:201], v[4:5] op_sel_hi:[0,1]
	v_pk_mul_f32 v[2:3], v[200:201], v[2:3] op_sel_hi:[0,1]
	v_cvt_f32_i32_e32 v53, v31
	v_cvt_f32_i32_e32 v50, v30
	v_cvt_f32_i32_e32 v36, v29
	v_cvt_f32_i32_e32 v37, v28
	ds_read_b128 v[28:31], v35
	s_waitcnt lgkmcnt(1)
; #define DF_EXP_A(p0, p1) do { _Pragma("unroll") for (int r = 0; r < 16; ++r) p0[r] = __builtin_amdgcn_exp2f(p0[r]); _Pragma("unroll") for (int r = 0; r < 8; ++r) p1[r] = __builtin_amdgcn_exp2f(p1[r]); } while (0)
; __device__ __forceinline__ void diff_unit(const PolDiff& P, LAS unsigned char* lds, const Ptrs& X) {
;     ...
;     DF_GLDS(0, 0); DF_GLDS(1, 1); __syncthreads();
;     P.cinit_abs<0>(pA0, DF_TL(0), wid, r32, hi); P.cinit_abs<1>(pA1, DF_TL(0), wid, r32, hi); DF_QK(pA0, pA1, 0); DF_EXP_A(pA0, pA1);
;     P.cinit_abs<0>(pB0, DF_TL(1), wid, r32, hi); P.cinit_abs<1>(pB1, DF_TL(1), wid, r32, hi);
	v_mfma_f32_32x32x16_bf16 v[2:17], v[20:23], v[140:143], v[2:17]
	v_bitop3_b32 v183, v0, v18, 64 bitop3:0x36
	v_add_u32_e32 v39, v182, v183
	v_and_b32_e32 v43, 0x7fffffff, v26
	v_and_b32_e32 v42, 0x7fffffff, v25
	v_and_b32_e32 v45, 0x7fffffff, v24
	ds_read_b128 v[24:27], v27 offset:8192
	ds_read_b128 v[20:23], v35 offset:8192
	v_and_b32_e32 v44, 0x7fffffff, v34
	v_and_b32_e32 v47, 0x7fffffff, v33
	v_and_b32_e32 v46, 0x7fffffff, v32
	ds_read_b128 v[32:35], v39
	s_waitcnt lgkmcnt(3)
	v_mfma_f32_32x32x16_bf16 v[2:17], v[28:31], v[136:139], v[2:17]
	v_and_b32_e32 v49, 0x7fffffff, v38
	v_and_b32_e32 v48, 0x7fffffff, v37
	v_and_b32_e32 v51, 0x7fffffff, v36
	ds_read_b128 v[28:31], v39 offset:8192
	v_and_b32_e32 v50, 0x7fffffff, v50
	v_and_b32_e32 v53, 0x7fffffff, v53
	v_and_b32_e32 v52, 0x7fffffff, v52
	s_waitcnt lgkmcnt(1)
	v_mfma_f32_32x32x16_bf16 v[2:17], v[32:35], v[132:135], v[2:17]
	v_and_b32_e32 v33, 0x7fffffff, v60
	v_and_b32_e32 v32, 0x7fffffff, v59
	v_mul_f32_e64 v94, v200, v32
	v_mul_f32_e64 v95, v200, v33
	v_mul_f32_e64 v92, v200, v52
	v_mul_f32_e64 v93, v200, v53
	v_pk_mul_f32 v[90:91], v[200:201], v[50:51] op_sel_hi:[0,1]
	v_pk_mul_f32 v[88:89], v[200:201], v[48:49] op_sel_hi:[0,1]
	v_pk_mul_f32 v[86:87], v[200:201], v[46:47] op_sel_hi:[0,1]
	v_pk_mul_f32 v[84:85], v[200:201], v[44:45] op_sel_hi:[0,1]
	v_pk_mul_f32 v[82:83], v[200:201], v[42:43] op_sel_hi:[0,1]
	v_pk_mul_f32 v[80:81], v[200:201], v[40:41] op_sel_hi:[0,1]
	s_movk_i32 s2, 0x60
	v_bitop3_b32 v185, v0, v18, s2 bitop3:0x36
	v_mfma_f32_32x32x16_bf16 v[80:95], v[24:27], v[140:143], v[80:95]
	v_add_u32_e32 v0, v182, v185
	ds_read_b128 v[36:39], v0
	ds_read_b128 v[32:35], v0 offset:8192
	v_and_b32_e32 v54, 24, v19
	v_and_b32_e32 v0, 0x100, v19
	v_add3_u32 v18, 0, v54, v55
	v_add3_u32 v184, v18, v56, v0
	v_mfma_f32_32x32x16_bf16 v[80:95], v[20:23], v[136:139], v[80:95]
	v_add_u32_e32 v0, 0xffffffbf, v57
	v_cvt_f32_i32_e32 v0, v0
	v_mov_b32_e32 v188, 0
	s_mov_b32 s66, 0x41200000
	s_mov_b32 s6, 0x41800000
	s_mov_b32 s0, 1
	s_mov_b32 s12, 2
	s_waitcnt lgkmcnt(1)
	v_mfma_f32_32x32x16_bf16 v[2:17], v[36:39], v[128:131], v[2:17]
	s_mov_b32 s1, 3
	v_mov_b32_e32 v202, v200
	v_mov_b32_e32 v203, v200
	v_add_u32_e32 v189, s42, v58
	v_add_u32_e32 v190, s42, v57
	s_mov_b32 s2, 0
	v_mov_b32_e32 v48, 0
	v_mfma_f32_32x32x16_bf16 v[80:95], v[28:31], v[132:135], v[80:95]
	s_nop 3
	v_exp_f32_e32 v178, v2
	v_exp_f32_e32 v180, v3
	v_exp_f32_e32 v174, v4
	v_exp_f32_e32 v176, v5
	v_exp_f32_e32 v170, v6
	v_exp_f32_e32 v172, v7
	v_exp_f32_e32 v166, v8
	v_exp_f32_e32 v168, v9
	v_exp_f32_e32 v152, v10
	v_exp_f32_e32 v156, v11
	v_exp_f32_e32 v154, v12
	v_exp_f32_e32 v158, v13
	v_exp_f32_e32 v162, v15
	v_exp_f32_e32 v160, v16
	v_subrev_u32_e32 v2, 64, v57
	v_add_u32_e32 v3, 0xffffffbd, v57
	v_add_u32_e32 v4, 0xffffffbe, v57
	v_add_u32_e32 v5, 0xffffffb7, v57
	v_add_u32_e32 v6, 0xffffffb8, v57
	v_add_u32_e32 v7, 0xffffffb5, v57
	v_add_u32_e32 v8, 0xffffffb6, v57
	v_add_u32_e32 v9, 0xffffffaf, v57
	v_add_u32_e32 v10, 0xffffffb0, v57
	v_add_u32_e32 v11, 0xffffffad, v57
	v_add_u32_e32 v12, 0xffffffae, v57
	v_add_u32_e32 v13, 0xffffffa7, v57
	v_add_u32_e32 v15, 0xffffffa8, v57
	v_add_u32_e32 v16, 0xffffffa5, v57
	v_exp_f32_e32 v164, v17
	s_waitcnt lgkmcnt(0)
; #define DF_EXP_A(p0, p1) do { _Pragma("unroll") for (int r = 0; r < 16; ++r) p0[r] = __builtin_amdgcn_exp2f(p0[r]); _Pragma("unroll") for (int r = 0; r < 8; ++r) p1[r] = __builtin_amdgcn_exp2f(p1[r]); } while (0)
;     template <int BLK> __device__ __forceinline__ void cinit_abs(f32x16& p, int t, int wid, int r32, int hi) const {
;         const float base = (float)(128 * qb + 32 * (wid & 3) + r32 - 64 * t - 4 * hi - 32 * BLK);
; #pragma unroll
;         for (int r = 0; r < 16; ++r) p[r] = nsl * fabsf(base - (float)((r & 3) + 8 * (r >> 2)));
;     }
; __device__ __forceinline__ void diff_unit(const PolDiff& P, LAS unsigned char* lds, const Ptrs& X) {
;     ...
;     float l_reg = 0.f; f32x16 o[NB];
; #pragma unroll
;     for (int d = 0; d < NB; ++d) o[d] = f32x16{};
;     f32x16 pA0, pA1, pB0, pB1; bf16x8 pa0, pa1, pa2, pa3, ka0, ka1, kb0, kb1;
;     int rp = 2, rc = 0, rn = 1;
;     DF_GLDS(0, 0); DF_GLDS(1, 1); __syncthreads();
;     P.cinit_abs<0>(pA0, DF_TL(0), wid, r32, hi); P.cinit_abs<1>(pA1, DF_TL(0), wid, r32, hi); DF_QK(pA0, pA1, 0); DF_EXP_A(pA0, pA1);
;     P.cinit_abs<0>(pB0, DF_TL(1), wid, r32, hi); P.cinit_abs<1>(pB1, DF_TL(1), wid, r32, hi);
	v_mfma_f32_32x32x16_bf16 v[80:95], v[32:35], v[128:131], v[80:95]
	v_add_u32_e32 v17, 0xffffffa6, v57
	v_cvt_f32_i32_e32 v19, v16
	v_cvt_f32_i32_e32 v15, v15
	v_cvt_f32_i32_e32 v16, v13
	v_cvt_f32_i32_e32 v12, v12
	v_cvt_f32_i32_e32 v13, v11
	v_cvt_f32_i32_e32 v10, v10
	v_cvt_f32_i32_e32 v11, v9
	v_cvt_f32_i32_e32 v8, v8
	v_cvt_f32_i32_e32 v9, v7
	v_cvt_f32_i32_e32 v6, v6
	v_cvt_f32_i32_e32 v7, v5
	v_cvt_f32_i32_e32 v2, v2
	v_cvt_f32_i32_e32 v5, v3
	v_cvt_f32_i32_e32 v4, v4
	v_cvt_f32_i32_e32 v18, v17
	v_and_b32_e32 v3, 0x7fffffff, v0
	v_and_b32_e32 v2, 0x7fffffff, v2
	v_and_b32_e32 v5, 0x7fffffff, v5
	v_and_b32_e32 v4, 0x7fffffff, v4
	v_and_b32_e32 v7, 0x7fffffff, v7
	v_and_b32_e32 v6, 0x7fffffff, v6
	v_and_b32_e32 v9, 0x7fffffff, v9
	v_and_b32_e32 v8, 0x7fffffff, v8
	v_and_b32_e32 v11, 0x7fffffff, v11
	v_and_b32_e32 v10, 0x7fffffff, v10
	v_and_b32_e32 v13, 0x7fffffff, v13
	v_and_b32_e32 v12, 0x7fffffff, v12
	v_and_b32_e32 v17, 0x7fffffff, v16
	v_and_b32_e32 v16, 0x7fffffff, v15
	v_and_b32_e32 v19, 0x7fffffff, v19
	v_and_b32_e32 v18, 0x7fffffff, v18
	v_pk_mul_f32 v[124:125], v[200:201], v[16:17] op_sel_hi:[0,1]
	v_pk_mul_f32 v[122:123], v[200:201], v[12:13] op_sel_hi:[0,1]
	v_pk_mul_f32 v[120:121], v[200:201], v[10:11] op_sel_hi:[0,1]
	v_pk_mul_f32 v[118:119], v[200:201], v[8:9] op_sel_hi:[0,1]
	v_pk_mul_f32 v[116:117], v[200:201], v[6:7] op_sel_hi:[0,1]
	v_pk_mul_f32 v[114:115], v[200:201], v[4:5] op_sel_hi:[0,1]
	v_pk_mul_f32 v[112:113], v[200:201], v[2:3] op_sel_hi:[0,1]
	v_add_u32_e32 v0, 0xffffffbf, v58
	v_subrev_u32_e32 v2, 64, v58
	v_add_u32_e32 v3, 0xffffffbd, v58
	v_add_u32_e32 v4, 0xffffffbe, v58
	v_add_u32_e32 v5, 0xffffffb7, v58
	v_add_u32_e32 v6, 0xffffffb8, v58
	v_add_u32_e32 v7, 0xffffffb5, v58
	v_add_u32_e32 v8, 0xffffffb6, v58
	v_add_u32_e32 v9, 0xffffffaf, v58
	v_add_u32_e32 v10, 0xffffffb0, v58
	v_add_u32_e32 v11, 0xffffffad, v58
	v_add_u32_e32 v12, 0xffffffae, v58
	v_add_u32_e32 v13, 0xffffffa7, v58
	v_add_u32_e32 v15, 0xffffffa8, v58
	v_add_u32_e32 v16, 0xffffffa5, v58
	v_add_u32_e32 v17, 0xffffffa6, v58
	v_pk_mul_f32 v[126:127], v[200:201], v[18:19] op_sel_hi:[0,1]
	v_cvt_f32_i32_e32 v18, v17
	v_cvt_f32_i32_e32 v19, v16
	v_cvt_f32_i32_e32 v15, v15
	v_cvt_f32_i32_e32 v16, v13
	v_cvt_f32_i32_e32 v12, v12
	v_cvt_f32_i32_e32 v13, v11
	v_cvt_f32_i32_e32 v10, v10
	v_cvt_f32_i32_e32 v11, v9
	v_cvt_f32_i32_e32 v8, v8
	v_cvt_f32_i32_e32 v9, v7
	v_cvt_f32_i32_e32 v6, v6
	v_cvt_f32_i32_e32 v7, v5
	v_cvt_f32_i32_e32 v0, v0
	v_cvt_f32_i32_e32 v2, v2
	v_cvt_f32_i32_e32 v5, v3
	v_cvt_f32_i32_e32 v4, v4
	v_exp_f32_e32 v14, v14
	v_exp_f32_e32 v80, v80
	v_exp_f32_e32 v81, v81
	v_exp_f32_e32 v82, v82
	v_exp_f32_e32 v83, v83
	v_exp_f32_e32 v84, v84
	v_exp_f32_e32 v85, v85
	v_exp_f32_e32 v86, v86
	v_exp_f32_e32 v87, v87
	v_and_b32_e32 v3, 0x7fffffff, v0
	v_and_b32_e32 v2, 0x7fffffff, v2
	v_and_b32_e32 v5, 0x7fffffff, v5
	v_and_b32_e32 v4, 0x7fffffff, v4
	v_and_b32_e32 v7, 0x7fffffff, v7
	v_and_b32_e32 v6, 0x7fffffff, v6
	v_and_b32_e32 v9, 0x7fffffff, v9
	v_and_b32_e32 v8, 0x7fffffff, v8
	v_and_b32_e32 v11, 0x7fffffff, v11
	v_and_b32_e32 v10, 0x7fffffff, v10
	v_and_b32_e32 v13, 0x7fffffff, v13
	v_and_b32_e32 v12, 0x7fffffff, v12
	v_and_b32_e32 v17, 0x7fffffff, v16
	v_and_b32_e32 v16, 0x7fffffff, v15
	v_and_b32_e32 v19, 0x7fffffff, v19
	v_and_b32_e32 v18, 0x7fffffff, v18
	v_pk_mul_f32 v[110:111], v[200:201], v[18:19] op_sel_hi:[0,1]
	v_pk_mul_f32 v[108:109], v[200:201], v[16:17] op_sel_hi:[0,1]
	v_pk_mul_f32 v[106:107], v[200:201], v[12:13] op_sel_hi:[0,1]
	v_pk_mul_f32 v[104:105], v[200:201], v[10:11] op_sel_hi:[0,1]
	v_pk_mul_f32 v[102:103], v[200:201], v[8:9] op_sel_hi:[0,1]
	v_pk_mul_f32 v[100:101], v[200:201], v[6:7] op_sel_hi:[0,1]
	v_pk_mul_f32 v[98:99], v[200:201], v[4:5] op_sel_hi:[0,1]
	v_pk_mul_f32 v[96:97], v[200:201], v[2:3] op_sel_hi:[0,1]
	v_mov_b32_e32 v49, v188
	v_mov_b32_e32 v50, v188
	v_mov_b32_e32 v51, v188
	v_mov_b32_e32 v52, v188
	v_mov_b32_e32 v53, v188
	v_mov_b32_e32 v54, v188
	v_mov_b32_e32 v55, v188
	v_mov_b32_e32 v56, v188
	v_mov_b32_e32 v57, v188
	v_mov_b32_e32 v58, v188
	v_mov_b32_e32 v59, v188
	v_mov_b32_e32 v60, v188
	v_mov_b32_e32 v61, v188
	v_mov_b32_e32 v62, v188
	v_mov_b32_e32 v63, v188
	v_mov_b32_e32 v64, 0
	v_mov_b32_e32 v65, v188
	v_mov_b32_e32 v66, v188
	v_mov_b32_e32 v67, v188
	v_mov_b32_e32 v68, v188
	v_mov_b32_e32 v69, v188
	v_mov_b32_e32 v70, v188
	v_mov_b32_e32 v71, v188
	v_mov_b32_e32 v72, v188
	v_mov_b32_e32 v73, v188
	v_mov_b32_e32 v74, v188
	v_mov_b32_e32 v75, v188
	v_mov_b32_e32 v76, v188
	v_mov_b32_e32 v77, v188
	v_mov_b32_e32 v78, v188
	v_mov_b32_e32 v79, v188
	v_mov_b32_e32 v16, 0
	v_mov_b32_e32 v17, v188
	v_mov_b32_e32 v18, v188
	v_mov_b32_e32 v19, v188
	v_mov_b32_e32 v20, v188
	v_mov_b32_e32 v21, v188
	v_mov_b32_e32 v22, v188
	v_mov_b32_e32 v23, v188
	v_mov_b32_e32 v24, v188
	v_mov_b32_e32 v25, v188
	v_mov_b32_e32 v26, v188
	v_mov_b32_e32 v27, v188
	v_mov_b32_e32 v28, v188
	v_mov_b32_e32 v29, v188
	v_mov_b32_e32 v30, v188
	v_mov_b32_e32 v31, v188
	v_mov_b32_e32 v32, 0
	v_mov_b32_e32 v33, v188
	v_mov_b32_e32 v34, v188
	v_mov_b32_e32 v35, v188
	v_mov_b32_e32 v36, v188
	v_mov_b32_e32 v37, v188
	v_mov_b32_e32 v38, v188
	v_mov_b32_e32 v39, v188
	v_mov_b32_e32 v40, v188
	v_mov_b32_e32 v41, v188
	v_mov_b32_e32 v42, v188
	v_mov_b32_e32 v43, v188
	v_mov_b32_e32 v44, v188
	v_mov_b32_e32 v45, v188
	v_mov_b32_e32 v46, v188
	v_mov_b32_e32 v47, v188
	s_mov_b32 s67, 0x41300000
	s_mov_b32 s7, 0x41880000
